# P2: each workgroup takes its three column tiles in an order rotated by (pn&3), so epilogue kinds are mixed within every round
# speedup vs baseline: 1.0055x; 1.0053x over previous
.LBB0_176:
	s_cmp_lt_i32 s26, 3
	s_cselect_b64 s[6:7], -1, 0
	s_and_b64 s[10:11], s[6:7], s[4:5]
	s_andn2_b64 vcc, exec, s[10:11]
	s_cbranch_vccnz .LBB0_291
	s_cmpk_lt_i32 s2, 0x300
	s_cselect_b64 s[4:5], -1, 0
	s_cmpk_gt_i32 s2, 0x2ff
	s_mov_b64 s[12:13], s[24:25]
	v_readfirstlane_b32 s22, v0
	s_cbranch_scc1 .LBB0_179
	s_ashr_i32 s6, s2, 31
	s_lshr_b32 s6, s6, 29
	s_add_i32 s6, s2, s6
	s_ashr_i32 s7, s6, 3
	s_and_b32 s6, s6, -8
	s_sub_i32 s6, s2, s6
	s_cmp_lt_i32 s6, 0
	s_movk_i32 s8, 0x61
	s_cselect_b32 s8, s8, 0x60
	s_mul_i32 s6, s6, s8
	s_add_i32 s6, s6, s7
	s_mul_hi_i32 s7, s6, 0x2aaaaaab
	s_lshr_b32 s8, s7, 31
	s_ashr_i32 s7, s7, 5
	s_add_i32 s7, s7, s8
	s_lshl_b32 s8, s7, 3
	s_mulk_i32 s7, 0xc0
	s_sub_i32 s7, s6, s7
	s_sext_i32_i16 s6, s7
	s_bfe_u32 s6, s6, 0x3001c
	s_add_i32 s6, s7, s6
	s_sext_i32_i16 s9, s6
	s_and_b32 s6, s6, 0xfff8
	s_sub_i32 s6, s7, s6
	s_sext_i32_i16 s6, s6
	s_add_i32 s6, s8, s6
	s_ashr_i32 s8, s9, 3
	s_add_i32 s9, s8, 4
	s_cmpk_gt_i32 s7, 0x5f
	s_cselect_b32 s62, s9, s8
	s_add_i32 s7, s62, 16
	s_sub_i32 s8, s62, 16
	s_sub_i32 s9, s62, 0
	s_cmp_lt_u32 s9, 4
	s_cselect_b32 s7, s7, s62
	s_sub_i32 s9, s62, 16
	s_cmp_lt_u32 s9, 4
	s_cselect_b32 s62, s8, s7
	s_and_b32 s7, s62, 3
	s_lshr_b32 s8, s62, 2
	s_cmp_eq_u32 s8, 0
	s_cselect_b32 s9, 1, 0
	s_cmp_ge_u32 s8, 5
	s_cselect_b32 s9, 1, s9
	s_and_b32 s8, s8, 3
	s_add_i32 s8, s8, s7
	s_cmp_ge_u32 s8, 3
	s_cselect_b32 s62, 3, 0
	s_sub_i32 s8, s8, s62
	s_lshl_b32 s9, s9, 2
	s_sub_i32 s62, 4, s9
	s_add_i32 s9, s8, s9
	s_cmp_eq_u32 s8, 0
	s_cselect_b32 s62, s62, s9
	s_lshl_b32 s62, s62, 2
	s_or_b32 s62, s62, s7

.LBB0_185:
	s_add_i32 s83, s83, 1
	s_mul_i32 s4, s83, s84
	s_mul_hi_u32 s5, s83, s3
	s_add_i32 s5, s5, s4
	s_mul_i32 s4, s83, s3
	s_add_u32 s58, s4, s2
	s_addc_u32 s59, s5, s85
	v_mov_b64_e32 v[2:3], 0x300
	v_cmp_lt_i64_e64 s[4:5], s[58:59], v[2:3]
	v_mov_b64_e32 v[2:3], 0x2ff
	v_cmp_gt_i64_e32 vcc, s[58:59], v[2:3]
	s_cbranch_vccnz .LBB0_187
	s_ashr_i32 s7, s58, 31
	s_lshr_b32 s7, s7, 29
	s_add_i32 s7, s58, s7
	s_ashr_i32 s54, s7, 3
	s_and_b32 s7, s7, -8
	s_sub_i32 s7, s58, s7
	s_cmp_lt_i32 s7, 0
	s_cselect_b32 s55, s88, 0x60
	s_mul_i32 s7, s7, s55
	s_add_i32 s7, s7, s54
	s_mul_hi_i32 s54, s7, 0x2aaaaaab
	s_lshr_b32 s55, s54, 31
	s_ashr_i32 s54, s54, 5
	s_add_i32 s54, s54, s55
	s_lshl_b32 s55, s54, 3
	s_sub_i32 s56, 32, s55
	s_min_i32 s56, s56, 8
	s_abs_i32 s57, s56
	v_cvt_f32_u32_e32 v2, s57
	s_sub_i32 s59, 0, s57
	s_mulk_i32 s54, 0xc0
	s_sub_i32 s7, s7, s54
	v_rcp_iflag_f32_e32 v2, v2
	s_abs_i32 s54, s7
	s_xor_b32 s58, s7, s56
	s_ashr_i32 s58, s58, 31
	v_mul_f32_e32 v2, 0x4f7ffffe, v2
	v_cvt_u32_f32_e32 v2, v2
	s_nop 0
	v_readfirstlane_b32 s60, v2
	s_mul_i32 s59, s59, s60
	s_mul_hi_u32 s59, s60, s59
	s_add_i32 s60, s60, s59
	s_mul_hi_u32 s59, s54, s60
	s_mul_i32 s60, s59, s57
	s_sub_i32 s54, s54, s60
	s_add_i32 s61, s59, 1
	s_sub_i32 s60, s54, s57
	s_cmp_ge_u32 s54, s57
	s_cselect_b32 s59, s61, s59
	s_cselect_b32 s54, s60, s54
	s_add_i32 s60, s59, 1
	s_cmp_ge_u32 s54, s57
	s_cselect_b32 s54, s60, s59
	s_xor_b32 s54, s54, s58
	s_sub_i32 s57, s54, s58
	s_mul_i32 s54, s57, s56
	s_sub_i32 s7, s7, s54
	s_add_i32 s54, s55, s7
	s_add_i32 s7, s57, 4
	s_cmp_gt_i32 s57, 11
	s_cselect_b32 s56, s7, s57
	s_add_i32 s57, s56, 16
	s_sub_i32 s58, s56, 16
	s_sub_i32 s59, s56, 0
	s_cmp_lt_u32 s59, 4
	s_cselect_b32 s57, s57, s56
	s_sub_i32 s59, s56, 16
	s_cmp_lt_u32 s59, 4
	s_cselect_b32 s56, s58, s57
	s_and_b32 s57, s56, 3
	s_lshr_b32 s58, s56, 2
	s_cmp_eq_u32 s58, 0
	s_cselect_b32 s59, 1, 0
	s_cmp_ge_u32 s58, 5
	s_cselect_b32 s59, 1, s59
	s_and_b32 s58, s58, 3
	s_add_i32 s58, s58, s57
	s_cmp_ge_u32 s58, 3
	s_cselect_b32 s56, 3, 0
	s_sub_i32 s58, s58, s56
	s_lshl_b32 s59, s59, 2
	s_sub_i32 s56, 4, s59
	s_add_i32 s59, s58, s59
	s_cmp_eq_u32 s58, 0
	s_cselect_b32 s56, s56, s59
	s_lshl_b32 s56, s56, 2
	s_or_b32 s56, s56, s57
